# EpiMla: rope cos/sin loads of a wave's 8 row blocks issued together at the first block (staged in dead K-loop fragment VGPRs) instead of 8 serialized load-wait pairs
# speedup vs baseline: 1.0152x; 1.0000x over previous
; __device__ __forceinline__ u32x2 pack4(f32x4 v) { u32x2 w; w.x = pk2(v[0], v[1]); w.y = pk2(v[2], v[3]); return w; }
;     __device__ __forceinline__ void operator()(const f32x4 (&acc)[2][2][4][2], const Unit& u, int wr, int wc, int fr, int fq) const {
;     ...
;                     if (rope) {
;                         const f32x4 c = *(const f32x4*)(cs + (size_t)row * 32 + 4 * fq), s = *(const f32x4*)(cs + (size_t)row * 32 + 16 + 4 * fq);
;                         const f32x4 a = v0 * c - v1 * s, b = v1 * c + v0 * s; v0 = a; v1 = b;
;                     }
;                     if (cgp < 12) { v0 = v0 * qs; v1 = v1 * qs; }
;                     const int bq = row >> 12, sq = row & (SEQ - 1);
;                     bf16_t* rowp;
;                     if (cgp < 12) rowp = O + ((size_t)(bq * 4 + cgp / 3) * SEQ + sq) * 96 + (cgp % 3) * 32 + 4 * fq;
;                     else if (cgp < 20) rowp = O + (size_t)T * 384 + ((size_t)(bq * 4 + (cgp - 12) / 2) * SEQ + sq) * 64 + ((cgp - 12) & 1) * 32 + 4 * fq;
;                     else rowp = O + (size_t)T * 640 + ((size_t)(bq * 4 + (cgp - 20) / 2) * SEQ + sq) * 64 + ((cgp - 20) & 1) * 32 + 4 * fq;
;                     if (cgp < 28) { *(u32x2*)(rowp) = pack4(v0); *(u32x2*)(rowp + 16) = pack4(v1); }
.LBB0_543:
	s_lshl_b32 s16, s16, 8
	s_add_i32 s16, s16, s59
	v_or_b32_e32 v146, s16, v139
	v_cndmask_b32_e64 v112, 0, 1, s[14:15]
	v_cmp_ne_u32_e64 s[12:13], 1, v112
	s_andn2_b64 vcc, exec, s[14:15]
	v_ashrrev_i32_e32 v147, 31, v146
	s_cbranch_vccnz .LBB0_545
	v_lshlrev_b64 v[148:149], 7, v[146:147]
	v_lshl_add_u64 v[148:149], v[140:141], 0, v[148:149]
	global_load_dwordx4 v[162:165], v[148:149], off offset:2112
	global_load_dwordx4 v[166:169], v[148:149], off offset:2048
	v_add_co_u32_e32 v190, vcc, 0x1000, v148
	v_addc_co_u32_e32 v191, vcc, 0, v149, vcc
	global_load_dwordx4 v[170:173], v[190:191], off offset:64
	global_load_dwordx4 v[174:177], v[190:191], off
	global_load_dwordx4 v[178:181], v[190:191], off offset:2112
	global_load_dwordx4 v[182:185], v[190:191], off offset:2048
	v_add_co_u32_e32 v190, vcc, 0x4000, v148
	v_addc_co_u32_e32 v191, vcc, 0, v149, vcc
	global_load_dwordx4 v[186:189], v[190:191], off offset:64
	global_load_dwordx4 v[198:201], v[190:191], off
	global_load_dwordx4 v[202:205], v[190:191], off offset:2112
	global_load_dwordx4 v[206:209], v[190:191], off offset:2048
	v_add_co_u32_e32 v190, vcc, 0x5000, v148
	v_addc_co_u32_e32 v191, vcc, 0, v149, vcc
	global_load_dwordx4 v[210:213], v[190:191], off offset:64
	global_load_dwordx4 v[214:217], v[190:191], off
	global_load_dwordx4 v[218:221], v[190:191], off offset:2112
	global_load_dwordx4 v[222:225], v[190:191], off offset:2048
	global_load_dwordx4 v[152:155], v[148:149], off offset:64
	global_load_dwordx4 v[156:159], v[148:149], off
	s_waitcnt vmcnt(0)
	v_pk_mul_f32 v[148:149], v[124:125], v[154:155]
	v_pk_mul_f32 v[160:161], v[122:123], v[152:153]
	v_pk_mul_f32 v[154:155], v[128:129], v[154:155]
	v_pk_mul_f32 v[152:153], v[126:127], v[152:153]
	v_pk_fma_f32 v[128:129], v[128:129], v[158:159], v[148:149] neg_lo:[0,0,1] neg_hi:[0,0,1]
	v_pk_fma_f32 v[126:127], v[126:127], v[156:157], v[160:161] neg_lo:[0,0,1] neg_hi:[0,0,1]
	v_pk_fma_f32 v[124:125], v[124:125], v[158:159], v[154:155]
	v_pk_fma_f32 v[122:123], v[122:123], v[156:157], v[152:153]

;     __device__ __forceinline__ void operator()(const f32x4 (&acc)[2][2][4][2], const Unit& u, int wr, int wc, int fr, int fq) const {
;     ...
;                     const int row = row0 + ai * HALF + m * 16;
;                     f32x4 v0 = acc[ai][bj][m][0], v1 = acc[ai][bj][m][1];
;                     if (rope) {
;                         const f32x4 c = *(const f32x4*)(cs + (size_t)row * 32 + 4 * fq), s = *(const f32x4*)(cs + (size_t)row * 32 + 16 + 4 * fq);
;                         const f32x4 a = v0 * c - v1 * s, b = v1 * c + v0 * s; v0 = a; v1 = b;
;                     }
.LBB0_555:
	v_or_b32_e32 v122, 16, v146
	s_and_b64 vcc, exec, s[12:13]
	v_ashrrev_i32_e32 v123, 31, v122
	s_cbranch_vccnz .LBB0_557
	v_lshlrev_b64 v[124:125], 7, v[122:123]
	v_lshl_add_u64 v[128:129], v[140:141], 0, v[124:125]
	v_mov_b32_e32 v124, v162
	v_mov_b32_e32 v125, v163
	v_mov_b32_e32 v126, v164
	v_mov_b32_e32 v127, v165
	v_mov_b32_e32 v154, v166
	v_mov_b32_e32 v155, v167
	v_mov_b32_e32 v156, v168
	v_mov_b32_e32 v157, v169
	v_pk_mul_f32 v[128:129], v[116:117], v[126:127]
	v_pk_mul_f32 v[148:149], v[114:115], v[124:125]
	v_pk_mul_f32 v[126:127], v[120:121], v[126:127]
	v_pk_mul_f32 v[124:125], v[118:119], v[124:125]
	v_pk_fma_f32 v[120:121], v[120:121], v[156:157], v[128:129] neg_lo:[0,0,1] neg_hi:[0,0,1]
	v_pk_fma_f32 v[118:119], v[118:119], v[154:155], v[148:149] neg_lo:[0,0,1] neg_hi:[0,0,1]
	v_pk_fma_f32 v[116:117], v[116:117], v[156:157], v[126:127]
	v_pk_fma_f32 v[114:115], v[114:115], v[154:155], v[124:125]

;     __device__ __forceinline__ void operator()(const f32x4 (&acc)[2][2][4][2], const Unit& u, int wr, int wc, int fr, int fq) const {
;     ...
;                     const int row = row0 + ai * HALF + m * 16;
;                     f32x4 v0 = acc[ai][bj][m][0], v1 = acc[ai][bj][m][1];
;                     if (rope) {
;                         const f32x4 c = *(const f32x4*)(cs + (size_t)row * 32 + 4 * fq), s = *(const f32x4*)(cs + (size_t)row * 32 + 16 + 4 * fq);
;                         const f32x4 a = v0 * c - v1 * s, b = v1 * c + v0 * s; v0 = a; v1 = b;
;                     }
.LBB0_561:
	v_lshlrev_b64 v[116:117], 7, v[114:115]
	v_lshl_add_u64 v[120:121], v[140:141], 0, v[116:117]
	v_mov_b32_e32 v116, v170
	v_mov_b32_e32 v117, v171
	v_mov_b32_e32 v118, v172
	v_mov_b32_e32 v119, v173
	v_mov_b32_e32 v154, v174
	v_mov_b32_e32 v155, v175
	v_mov_b32_e32 v156, v176
	v_mov_b32_e32 v157, v177
	v_pk_mul_f32 v[120:121], v[106:107], v[118:119]
	v_pk_mul_f32 v[124:125], v[104:105], v[116:117]
	v_pk_mul_f32 v[118:119], v[110:111], v[118:119]
	v_pk_mul_f32 v[116:117], v[108:109], v[116:117]
	v_pk_fma_f32 v[110:111], v[110:111], v[156:157], v[120:121] neg_lo:[0,0,1] neg_hi:[0,0,1]
	v_pk_fma_f32 v[108:109], v[108:109], v[154:155], v[124:125] neg_lo:[0,0,1] neg_hi:[0,0,1]
	v_pk_fma_f32 v[106:107], v[106:107], v[156:157], v[118:119]
	v_pk_fma_f32 v[104:105], v[104:105], v[154:155], v[116:117]

;     __device__ __forceinline__ void operator()(const f32x4 (&acc)[2][2][4][2], const Unit& u, int wr, int wc, int fr, int fq) const {
;     ...
;                     const int row = row0 + ai * HALF + m * 16;
;                     f32x4 v0 = acc[ai][bj][m][0], v1 = acc[ai][bj][m][1];
;                     if (rope) {
;                         const f32x4 c = *(const f32x4*)(cs + (size_t)row * 32 + 4 * fq), s = *(const f32x4*)(cs + (size_t)row * 32 + 16 + 4 * fq);
;                         const f32x4 a = v0 * c - v1 * s, b = v1 * c + v0 * s; v0 = a; v1 = b;
;                     }
.LBB0_566:
	v_lshlrev_b64 v[106:107], 7, v[104:105]
	v_lshl_add_u64 v[110:111], v[140:141], 0, v[106:107]
	v_mov_b32_e32 v106, v178
	v_mov_b32_e32 v107, v179
	v_mov_b32_e32 v108, v180
	v_mov_b32_e32 v109, v181
	v_mov_b32_e32 v154, v182
	v_mov_b32_e32 v155, v183
	v_mov_b32_e32 v156, v184
	v_mov_b32_e32 v157, v185
	v_pk_mul_f32 v[110:111], v[98:99], v[108:109]
	v_pk_mul_f32 v[116:117], v[96:97], v[106:107]
	v_pk_mul_f32 v[108:109], v[102:103], v[108:109]
	v_pk_mul_f32 v[106:107], v[100:101], v[106:107]
	v_pk_fma_f32 v[102:103], v[102:103], v[156:157], v[110:111] neg_lo:[0,0,1] neg_hi:[0,0,1]
	v_pk_fma_f32 v[100:101], v[100:101], v[154:155], v[116:117] neg_lo:[0,0,1] neg_hi:[0,0,1]
	v_pk_fma_f32 v[98:99], v[98:99], v[156:157], v[108:109]
	v_pk_fma_f32 v[96:97], v[96:97], v[154:155], v[106:107]

;     __device__ __forceinline__ void operator()(const f32x4 (&acc)[2][2][4][2], const Unit& u, int wr, int wc, int fr, int fq) const {
;     ...
;                     const int row = row0 + ai * HALF + m * 16;
;                     f32x4 v0 = acc[ai][bj][m][0], v1 = acc[ai][bj][m][1];
;                     if (rope) {
;                         const f32x4 c = *(const f32x4*)(cs + (size_t)row * 32 + 4 * fq), s = *(const f32x4*)(cs + (size_t)row * 32 + 16 + 4 * fq);
;                         const f32x4 a = v0 * c - v1 * s, b = v1 * c + v0 * s; v0 = a; v1 = b;
;                     }
.LBB0_571:
	v_lshlrev_b64 v[98:99], 7, v[96:97]
	v_lshl_add_u64 v[102:103], v[140:141], 0, v[98:99]
	v_mov_b32_e32 v98, v186
	v_mov_b32_e32 v99, v187
	v_mov_b32_e32 v100, v188
	v_mov_b32_e32 v101, v189
	v_mov_b32_e32 v154, v198
	v_mov_b32_e32 v155, v199
	v_mov_b32_e32 v156, v200
	v_mov_b32_e32 v157, v201
	v_pk_mul_f32 v[102:103], v[90:91], v[100:101]
	v_pk_mul_f32 v[106:107], v[88:89], v[98:99]
	v_pk_mul_f32 v[100:101], v[94:95], v[100:101]
	v_pk_mul_f32 v[98:99], v[92:93], v[98:99]
	v_pk_fma_f32 v[94:95], v[94:95], v[156:157], v[102:103] neg_lo:[0,0,1] neg_hi:[0,0,1]
	v_pk_fma_f32 v[92:93], v[92:93], v[154:155], v[106:107] neg_lo:[0,0,1] neg_hi:[0,0,1]
	v_pk_fma_f32 v[90:91], v[90:91], v[156:157], v[100:101]
	v_pk_fma_f32 v[88:89], v[88:89], v[154:155], v[98:99]

;     __device__ __forceinline__ void operator()(const f32x4 (&acc)[2][2][4][2], const Unit& u, int wr, int wc, int fr, int fq) const {
;     ...
;                     const int row = row0 + ai * HALF + m * 16;
;                     f32x4 v0 = acc[ai][bj][m][0], v1 = acc[ai][bj][m][1];
;                     if (rope) {
;                         const f32x4 c = *(const f32x4*)(cs + (size_t)row * 32 + 4 * fq), s = *(const f32x4*)(cs + (size_t)row * 32 + 16 + 4 * fq);
;                         const f32x4 a = v0 * c - v1 * s, b = v1 * c + v0 * s; v0 = a; v1 = b;
;                     }
.LBB0_581:
	v_lshlrev_b64 v[90:91], 7, v[88:89]
	v_lshl_add_u64 v[94:95], v[140:141], 0, v[90:91]
	v_mov_b32_e32 v90, v202
	v_mov_b32_e32 v91, v203
	v_mov_b32_e32 v92, v204
	v_mov_b32_e32 v93, v205
	v_mov_b32_e32 v154, v206
	v_mov_b32_e32 v155, v207
	v_mov_b32_e32 v156, v208
	v_mov_b32_e32 v157, v209
	v_pk_mul_f32 v[94:95], v[82:83], v[92:93]
	v_pk_mul_f32 v[106:107], v[80:81], v[90:91]
	v_pk_mul_f32 v[92:93], v[86:87], v[92:93]
	v_pk_mul_f32 v[90:91], v[84:85], v[90:91]
	v_pk_fma_f32 v[86:87], v[86:87], v[156:157], v[94:95] neg_lo:[0,0,1] neg_hi:[0,0,1]
	v_pk_fma_f32 v[84:85], v[84:85], v[154:155], v[106:107] neg_lo:[0,0,1] neg_hi:[0,0,1]
	v_pk_fma_f32 v[82:83], v[82:83], v[156:157], v[92:93]
	v_pk_fma_f32 v[80:81], v[80:81], v[154:155], v[90:91]

;     __device__ __forceinline__ void operator()(const f32x4 (&acc)[2][2][4][2], const Unit& u, int wr, int wc, int fr, int fq) const {
;     ...
;                     const int row = row0 + ai * HALF + m * 16;
;                     f32x4 v0 = acc[ai][bj][m][0], v1 = acc[ai][bj][m][1];
;                     if (rope) {
;                         const f32x4 c = *(const f32x4*)(cs + (size_t)row * 32 + 4 * fq), s = *(const f32x4*)(cs + (size_t)row * 32 + 16 + 4 * fq);
;                         const f32x4 a = v0 * c - v1 * s, b = v1 * c + v0 * s; v0 = a; v1 = b;
;                     }
.LBB0_586:
	v_lshlrev_b64 v[82:83], 7, v[80:81]
	v_lshl_add_u64 v[86:87], v[140:141], 0, v[82:83]
	v_mov_b32_e32 v82, v210
	v_mov_b32_e32 v83, v211
	v_mov_b32_e32 v84, v212
	v_mov_b32_e32 v85, v213
	v_mov_b32_e32 v154, v214
	v_mov_b32_e32 v155, v215
	v_mov_b32_e32 v156, v216
	v_mov_b32_e32 v157, v217
	v_pk_mul_f32 v[86:87], v[74:75], v[84:85]
	v_pk_mul_f32 v[90:91], v[72:73], v[82:83]
	v_pk_mul_f32 v[84:85], v[78:79], v[84:85]
	v_pk_mul_f32 v[82:83], v[76:77], v[82:83]
	v_pk_fma_f32 v[78:79], v[78:79], v[156:157], v[86:87] neg_lo:[0,0,1] neg_hi:[0,0,1]
	v_pk_fma_f32 v[76:77], v[76:77], v[154:155], v[90:91] neg_lo:[0,0,1] neg_hi:[0,0,1]
	v_pk_fma_f32 v[74:75], v[74:75], v[156:157], v[84:85]
	v_pk_fma_f32 v[72:73], v[72:73], v[154:155], v[82:83]

;     __device__ __forceinline__ void operator()(const f32x4 (&acc)[2][2][4][2], const Unit& u, int wr, int wc, int fr, int fq) const {
;     ...
;                     const int row = row0 + ai * HALF + m * 16;
;                     f32x4 v0 = acc[ai][bj][m][0], v1 = acc[ai][bj][m][1];
;                     if (rope) {
;                         const f32x4 c = *(const f32x4*)(cs + (size_t)row * 32 + 4 * fq), s = *(const f32x4*)(cs + (size_t)row * 32 + 16 + 4 * fq);
;                         const f32x4 a = v0 * c - v1 * s, b = v1 * c + v0 * s; v0 = a; v1 = b;
;                     }
.LBB0_591:
	v_lshlrev_b64 v[74:75], 7, v[72:73]
	v_lshl_add_u64 v[78:79], v[140:141], 0, v[74:75]
	v_mov_b32_e32 v74, v218
	v_mov_b32_e32 v75, v219
	v_mov_b32_e32 v76, v220
	v_mov_b32_e32 v77, v221
	v_mov_b32_e32 v154, v222
	v_mov_b32_e32 v155, v223
	v_mov_b32_e32 v156, v224
	v_mov_b32_e32 v157, v225
	v_pk_mul_f32 v[78:79], v[66:67], v[76:77]
	v_pk_mul_f32 v[82:83], v[64:65], v[74:75]
	v_pk_mul_f32 v[76:77], v[70:71], v[76:77]
	v_pk_mul_f32 v[74:75], v[68:69], v[74:75]
	v_pk_fma_f32 v[70:71], v[70:71], v[156:157], v[78:79] neg_lo:[0,0,1] neg_hi:[0,0,1]
	v_pk_fma_f32 v[68:69], v[68:69], v[154:155], v[82:83] neg_lo:[0,0,1] neg_hi:[0,0,1]
	v_pk_fma_f32 v[66:67], v[66:67], v[156:157], v[76:77]
	v_pk_fma_f32 v[64:65], v[64:65], v[154:155], v[74:75]

;     __device__ __forceinline__ void operator()(const f32x4 (&acc)[2][2][4][2], const Unit& u, int wr, int wc, int fr, int fq) const {
;     ...
;                     if (rope) {
;                         const f32x4 c = *(const f32x4*)(cs + (size_t)row * 32 + 4 * fq), s = *(const f32x4*)(cs + (size_t)row * 32 + 16 + 4 * fq);
;                         const f32x4 a = v0 * c - v1 * s, b = v1 * c + v0 * s; v0 = a; v1 = b;
;                     }
.LBB0_599:
	v_lshlrev_b64 v[64:65], 7, v[146:147]
	v_lshl_add_u64 v[68:69], v[140:141], 0, v[64:65]
	global_load_dwordx4 v[162:165], v[68:69], off offset:2112
	global_load_dwordx4 v[166:169], v[68:69], off offset:2048
	v_add_co_u32_e32 v190, vcc, 0x1000, v68
	v_addc_co_u32_e32 v191, vcc, 0, v69, vcc
	global_load_dwordx4 v[170:173], v[190:191], off offset:64
	global_load_dwordx4 v[174:177], v[190:191], off
	global_load_dwordx4 v[178:181], v[190:191], off offset:2112
	global_load_dwordx4 v[182:185], v[190:191], off offset:2048
	v_add_co_u32_e32 v190, vcc, 0x4000, v68
	v_addc_co_u32_e32 v191, vcc, 0, v69, vcc
	global_load_dwordx4 v[186:189], v[190:191], off offset:64
	global_load_dwordx4 v[198:201], v[190:191], off
	global_load_dwordx4 v[202:205], v[190:191], off offset:2112
	global_load_dwordx4 v[206:209], v[190:191], off offset:2048
	v_add_co_u32_e32 v190, vcc, 0x5000, v68
	v_addc_co_u32_e32 v191, vcc, 0, v69, vcc
	global_load_dwordx4 v[210:213], v[190:191], off offset:64
	global_load_dwordx4 v[214:217], v[190:191], off
	global_load_dwordx4 v[218:221], v[190:191], off offset:2112
	global_load_dwordx4 v[222:225], v[190:191], off offset:2048
	global_load_dwordx4 v[64:67], v[68:69], off offset:64
	s_nop 0
	global_load_dwordx4 v[68:71], v[68:69], off
	s_waitcnt vmcnt(0)
	v_pk_mul_f32 v[74:75], v[58:59], v[66:67]
	v_pk_mul_f32 v[78:79], v[56:57], v[64:65]
	v_pk_mul_f32 v[66:67], v[62:63], v[66:67]
	v_pk_mul_f32 v[64:65], v[60:61], v[64:65]
	v_pk_fma_f32 v[62:63], v[62:63], v[70:71], v[74:75] neg_lo:[0,0,1] neg_hi:[0,0,1]
	v_pk_fma_f32 v[60:61], v[60:61], v[68:69], v[78:79] neg_lo:[0,0,1] neg_hi:[0,0,1]
	v_pk_fma_f32 v[58:59], v[58:59], v[70:71], v[66:67]
	v_pk_fma_f32 v[56:57], v[56:57], v[68:69], v[64:65]

;     __device__ __forceinline__ void operator()(const f32x4 (&acc)[2][2][4][2], const Unit& u, int wr, int wc, int fr, int fq) const {
;     ...
;                     const int row = row0 + ai * HALF + m * 16;
;                     f32x4 v0 = acc[ai][bj][m][0], v1 = acc[ai][bj][m][1];
;                     if (rope) {
;                         const f32x4 c = *(const f32x4*)(cs + (size_t)row * 32 + 4 * fq), s = *(const f32x4*)(cs + (size_t)row * 32 + 16 + 4 * fq);
;                         const f32x4 a = v0 * c - v1 * s, b = v1 * c + v0 * s; v0 = a; v1 = b;
;                     }
.LBB0_621:
	v_lshlrev_b64 v[32:33], 7, v[96:97]
	v_lshl_add_u64 v[36:37], v[140:141], 0, v[32:33]
	v_mov_b32_e32 v32, v186
	v_mov_b32_e32 v33, v187
	v_mov_b32_e32 v34, v188
	v_mov_b32_e32 v35, v189
	v_mov_b32_e32 v36, v198
	v_mov_b32_e32 v37, v199
	v_mov_b32_e32 v38, v200
	v_mov_b32_e32 v39, v201
	v_pk_mul_f32 v[40:41], v[26:27], v[34:35]
	v_pk_mul_f32 v[42:43], v[24:25], v[32:33]
	v_pk_mul_f32 v[34:35], v[30:31], v[34:35]
	v_pk_mul_f32 v[32:33], v[28:29], v[32:33]
	v_pk_fma_f32 v[30:31], v[30:31], v[38:39], v[40:41] neg_lo:[0,0,1] neg_hi:[0,0,1]
	v_pk_fma_f32 v[28:29], v[28:29], v[36:37], v[42:43] neg_lo:[0,0,1] neg_hi:[0,0,1]
	v_pk_fma_f32 v[26:27], v[26:27], v[38:39], v[34:35]
	v_pk_fma_f32 v[24:25], v[24:25], v[36:37], v[32:33]

;     __device__ __forceinline__ void operator()(const f32x4 (&acc)[2][2][4][2], const Unit& u, int wr, int wc, int fr, int fq) const {
;     ...
;                     const int row = row0 + ai * HALF + m * 16;
;                     f32x4 v0 = acc[ai][bj][m][0], v1 = acc[ai][bj][m][1];
;                     if (rope) {
;                         const f32x4 c = *(const f32x4*)(cs + (size_t)row * 32 + 4 * fq), s = *(const f32x4*)(cs + (size_t)row * 32 + 16 + 4 * fq);
;                         const f32x4 a = v0 * c - v1 * s, b = v1 * c + v0 * s; v0 = a; v1 = b;
;                     }
.LBB0_690:
	v_lshlrev_b64 v[56:57], 7, v[122:123]
	v_lshl_add_u64 v[60:61], v[140:141], 0, v[56:57]
	v_mov_b32_e32 v56, v162
	v_mov_b32_e32 v57, v163
	v_mov_b32_e32 v58, v164
	v_mov_b32_e32 v59, v165
	v_mov_b32_e32 v60, v166
	v_mov_b32_e32 v61, v167
	v_mov_b32_e32 v62, v168
	v_mov_b32_e32 v63, v169
	v_pk_mul_f32 v[64:65], v[50:51], v[58:59]
	v_pk_mul_f32 v[66:67], v[48:49], v[56:57]
	v_pk_mul_f32 v[58:59], v[54:55], v[58:59]
	v_pk_mul_f32 v[56:57], v[52:53], v[56:57]
	v_pk_fma_f32 v[54:55], v[54:55], v[62:63], v[64:65] neg_lo:[0,0,1] neg_hi:[0,0,1]
	v_pk_fma_f32 v[52:53], v[52:53], v[60:61], v[66:67] neg_lo:[0,0,1] neg_hi:[0,0,1]
	v_pk_fma_f32 v[50:51], v[50:51], v[62:63], v[58:59]
	v_pk_fma_f32 v[48:49], v[48:49], v[60:61], v[56:57]
	s_and_b64 vcc, exec, s[16:17]
	s_mov_b64 s[18:19], -1
	s_cbranch_vccnz .LBB0_610

;     __device__ __forceinline__ void operator()(const f32x4 (&acc)[2][2][4][2], const Unit& u, int wr, int wc, int fr, int fq) const {
;     ...
;                     const int row = row0 + ai * HALF + m * 16;
;                     f32x4 v0 = acc[ai][bj][m][0], v1 = acc[ai][bj][m][1];
;                     if (rope) {
;                         const f32x4 c = *(const f32x4*)(cs + (size_t)row * 32 + 4 * fq), s = *(const f32x4*)(cs + (size_t)row * 32 + 16 + 4 * fq);
;                         const f32x4 a = v0 * c - v1 * s, b = v1 * c + v0 * s; v0 = a; v1 = b;
;                     }
.LBB0_698:
	v_lshlrev_b64 v[48:49], 7, v[114:115]
	v_lshl_add_u64 v[52:53], v[140:141], 0, v[48:49]
	v_mov_b32_e32 v48, v170
	v_mov_b32_e32 v49, v171
	v_mov_b32_e32 v50, v172
	v_mov_b32_e32 v51, v173
	v_mov_b32_e32 v52, v174
	v_mov_b32_e32 v53, v175
	v_mov_b32_e32 v54, v176
	v_mov_b32_e32 v55, v177
	v_pk_mul_f32 v[56:57], v[42:43], v[50:51]
	v_pk_mul_f32 v[58:59], v[40:41], v[48:49]
	v_pk_mul_f32 v[50:51], v[46:47], v[50:51]
	v_pk_mul_f32 v[48:49], v[44:45], v[48:49]
	v_pk_fma_f32 v[46:47], v[46:47], v[54:55], v[56:57] neg_lo:[0,0,1] neg_hi:[0,0,1]
	v_pk_fma_f32 v[44:45], v[44:45], v[52:53], v[58:59] neg_lo:[0,0,1] neg_hi:[0,0,1]
	v_pk_fma_f32 v[42:43], v[42:43], v[54:55], v[50:51]
	v_pk_fma_f32 v[40:41], v[40:41], v[52:53], v[48:49]
	s_and_b64 vcc, exec, s[16:17]
	s_mov_b64 s[4:5], -1
	s_cbranch_vccnz .LBB0_614

;     __device__ __forceinline__ void operator()(const f32x4 (&acc)[2][2][4][2], const Unit& u, int wr, int wc, int fr, int fq) const {
;     ...
;                     const int row = row0 + ai * HALF + m * 16;
;                     f32x4 v0 = acc[ai][bj][m][0], v1 = acc[ai][bj][m][1];
;                     if (rope) {
;                         const f32x4 c = *(const f32x4*)(cs + (size_t)row * 32 + 4 * fq), s = *(const f32x4*)(cs + (size_t)row * 32 + 16 + 4 * fq);
;                         const f32x4 a = v0 * c - v1 * s, b = v1 * c + v0 * s; v0 = a; v1 = b;
;                     }
.LBB0_706:
	v_lshlrev_b64 v[40:41], 7, v[104:105]
	v_lshl_add_u64 v[44:45], v[140:141], 0, v[40:41]
	v_mov_b32_e32 v40, v178
	v_mov_b32_e32 v41, v179
	v_mov_b32_e32 v42, v180
	v_mov_b32_e32 v43, v181
	v_mov_b32_e32 v44, v182
	v_mov_b32_e32 v45, v183
	v_mov_b32_e32 v46, v184
	v_mov_b32_e32 v47, v185
	v_pk_mul_f32 v[48:49], v[34:35], v[42:43]
	v_pk_mul_f32 v[50:51], v[32:33], v[40:41]
	v_pk_mul_f32 v[42:43], v[38:39], v[42:43]
	v_pk_mul_f32 v[40:41], v[36:37], v[40:41]
	v_pk_fma_f32 v[38:39], v[38:39], v[46:47], v[48:49] neg_lo:[0,0,1] neg_hi:[0,0,1]
	v_pk_fma_f32 v[36:37], v[36:37], v[44:45], v[50:51] neg_lo:[0,0,1] neg_hi:[0,0,1]
	v_pk_fma_f32 v[34:35], v[34:35], v[46:47], v[42:43]
	v_pk_fma_f32 v[32:33], v[32:33], v[44:45], v[40:41]
	s_and_b64 vcc, exec, s[16:17]
	s_mov_b64 s[4:5], -1
	s_cbranch_vccnz .LBB0_618

;     __device__ __forceinline__ void operator()(const f32x4 (&acc)[2][2][4][2], const Unit& u, int wr, int wc, int fr, int fq) const {
;     ...
;                     const int row = row0 + ai * HALF + m * 16;
;                     f32x4 v0 = acc[ai][bj][m][0], v1 = acc[ai][bj][m][1];
;                     if (rope) {
;                         const f32x4 c = *(const f32x4*)(cs + (size_t)row * 32 + 4 * fq), s = *(const f32x4*)(cs + (size_t)row * 32 + 16 + 4 * fq);
;                         const f32x4 a = v0 * c - v1 * s, b = v1 * c + v0 * s; v0 = a; v1 = b;
;                     }
.LBB0_716:
	v_lshlrev_b64 v[24:25], 7, v[88:89]
	v_lshl_add_u64 v[28:29], v[140:141], 0, v[24:25]
	v_mov_b32_e32 v24, v202
	v_mov_b32_e32 v25, v203
	v_mov_b32_e32 v26, v204
	v_mov_b32_e32 v27, v205
	v_mov_b32_e32 v28, v206
	v_mov_b32_e32 v29, v207
	v_mov_b32_e32 v30, v208
	v_mov_b32_e32 v31, v209
	v_pk_mul_f32 v[38:39], v[18:19], v[26:27]
	v_pk_mul_f32 v[40:41], v[16:17], v[24:25]
	v_pk_mul_f32 v[26:27], v[22:23], v[26:27]
	v_pk_mul_f32 v[24:25], v[20:21], v[24:25]
	v_pk_fma_f32 v[22:23], v[22:23], v[30:31], v[38:39] neg_lo:[0,0,1] neg_hi:[0,0,1]
	v_pk_fma_f32 v[20:21], v[20:21], v[28:29], v[40:41] neg_lo:[0,0,1] neg_hi:[0,0,1]
	v_pk_fma_f32 v[18:19], v[18:19], v[30:31], v[26:27]
	v_pk_fma_f32 v[16:17], v[16:17], v[28:29], v[24:25]
	s_and_b64 vcc, exec, s[16:17]
	s_mov_b64 s[4:5], -1
	s_cbranch_vccnz .LBB0_632

;     __device__ __forceinline__ void operator()(const f32x4 (&acc)[2][2][4][2], const Unit& u, int wr, int wc, int fr, int fq) const {
;     ...
;                     const int row = row0 + ai * HALF + m * 16;
;                     f32x4 v0 = acc[ai][bj][m][0], v1 = acc[ai][bj][m][1];
;                     if (rope) {
;                         const f32x4 c = *(const f32x4*)(cs + (size_t)row * 32 + 4 * fq), s = *(const f32x4*)(cs + (size_t)row * 32 + 16 + 4 * fq);
;                         const f32x4 a = v0 * c - v1 * s, b = v1 * c + v0 * s; v0 = a; v1 = b;
;                     }
.LBB0_724:
	v_lshlrev_b64 v[16:17], 7, v[80:81]
	v_lshl_add_u64 v[20:21], v[140:141], 0, v[16:17]
	v_mov_b32_e32 v16, v210
	v_mov_b32_e32 v17, v211
	v_mov_b32_e32 v18, v212
	v_mov_b32_e32 v19, v213
	v_mov_b32_e32 v20, v214
	v_mov_b32_e32 v21, v215
	v_mov_b32_e32 v22, v216
	v_mov_b32_e32 v23, v217
	v_pk_mul_f32 v[24:25], v[10:11], v[18:19]
	v_pk_mul_f32 v[26:27], v[8:9], v[16:17]
	v_pk_mul_f32 v[18:19], v[14:15], v[18:19]
	v_pk_mul_f32 v[16:17], v[12:13], v[16:17]
	v_pk_fma_f32 v[14:15], v[14:15], v[22:23], v[24:25] neg_lo:[0,0,1] neg_hi:[0,0,1]
	v_pk_fma_f32 v[12:13], v[12:13], v[20:21], v[26:27] neg_lo:[0,0,1] neg_hi:[0,0,1]
	v_pk_fma_f32 v[10:11], v[10:11], v[22:23], v[18:19]
	v_pk_fma_f32 v[8:9], v[8:9], v[20:21], v[16:17]
	s_and_b64 vcc, exec, s[16:17]
	s_mov_b64 s[4:5], -1
	s_cbranch_vccnz .LBB0_636

;     __device__ __forceinline__ void operator()(const f32x4 (&acc)[2][2][4][2], const Unit& u, int wr, int wc, int fr, int fq) const {
;     ...
;                     const int row = row0 + ai * HALF + m * 16;
;                     f32x4 v0 = acc[ai][bj][m][0], v1 = acc[ai][bj][m][1];
;                     if (rope) {
;                         const f32x4 c = *(const f32x4*)(cs + (size_t)row * 32 + 4 * fq), s = *(const f32x4*)(cs + (size_t)row * 32 + 16 + 4 * fq);
;                         const f32x4 a = v0 * c - v1 * s, b = v1 * c + v0 * s; v0 = a; v1 = b;
;                     }
.LBB0_732:
	v_lshlrev_b64 v[8:9], 7, v[72:73]
	v_lshl_add_u64 v[12:13], v[140:141], 0, v[8:9]
	v_mov_b32_e32 v8, v218
	v_mov_b32_e32 v9, v219
	v_mov_b32_e32 v10, v220
	v_mov_b32_e32 v11, v221
	v_mov_b32_e32 v12, v222
	v_mov_b32_e32 v13, v223
	v_mov_b32_e32 v14, v224
	v_mov_b32_e32 v15, v225
	v_pk_mul_f32 v[16:17], v[2:3], v[10:11]
	v_pk_mul_f32 v[18:19], v[0:1], v[8:9]
	v_pk_mul_f32 v[10:11], v[6:7], v[10:11]
	v_pk_mul_f32 v[8:9], v[4:5], v[8:9]
	v_pk_fma_f32 v[6:7], v[6:7], v[14:15], v[16:17] neg_lo:[0,0,1] neg_hi:[0,0,1]
	v_pk_fma_f32 v[4:5], v[4:5], v[12:13], v[18:19] neg_lo:[0,0,1] neg_hi:[0,0,1]
	v_pk_fma_f32 v[2:3], v[2:3], v[14:15], v[10:11]
	v_pk_fma_f32 v[0:1], v[0:1], v[12:13], v[8:9]
	s_and_b64 vcc, exec, s[16:17]
	s_mov_b64 s[4:5], -1
	s_cbranch_vccnz .LBB0_640
